# g3 f32-MFMA loops: all operand ds_reads of an iteration issued up front into distinct registers with counted lgkmcnt waits (lever 8: next fragment's reads in the MFMA shadow)
# baseline (speedup 1.0000x reference)
.LBB0_2958:
	v_add_u32_e32 v22, s5, v18
	ds_read2_b32 v[20:21], v22 offset1:2
	v_add_u32_e32 v23, s5, v19
	v_add_u32_e32 v24, 0x14300, v23
	v_add_u32_e32 v25, 0x14700, v23
	v_add_u32_e32 v26, 0x14b00, v23
	v_add_u32_e32 v27, 0x14f00, v23
	v_add_u32_e32 v28, 0x15300, v23
	v_add_u32_e32 v29, 0x15700, v23
	v_add_u32_e32 v30, 0x15b00, v23
	v_add_u32_e32 v23, 0x15f00, v23
	ds_read_b32 v24, v24
	ds_read_b32 v25, v25
	ds_read_b32 v26, v26
	ds_read_b32 v27, v27
	ds_read_b32 v28, v28
	ds_read_b32 v29, v29
	ds_read_b32 v30, v30
	ds_read_b32 v23, v23
	ds_read2_b32 v[120:121], v22 offset0:4 offset1:6
	ds_read2_b32 v[122:123], v22 offset0:8 offset1:10
	ds_read2_b32 v[124:125], v22 offset0:12 offset1:14
	s_waitcnt lgkmcnt(10)
	v_mfma_f32_32x32x2_f32 v[2:17], v20, v24, v[2:17]
	s_add_i32 s8, s8, -8
	v_add_u32_e32 v19, 0x2000, v19
	s_cmp_eq_u32 s8, 0
	v_add_u32_e32 v18, 64, v18
	s_waitcnt lgkmcnt(9)
	v_mfma_f32_32x32x2_f32 v[2:17], v21, v25, v[2:17]
	s_waitcnt lgkmcnt(2)
	v_mfma_f32_32x32x2_f32 v[2:17], v120, v26, v[2:17]
	v_mfma_f32_32x32x2_f32 v[2:17], v121, v27, v[2:17]
	s_waitcnt lgkmcnt(1)
	v_mfma_f32_32x32x2_f32 v[2:17], v122, v28, v[2:17]
	v_mfma_f32_32x32x2_f32 v[2:17], v123, v29, v[2:17]
	s_waitcnt lgkmcnt(0)
	v_mfma_f32_32x32x2_f32 v[2:17], v124, v30, v[2:17]
	v_mfma_f32_32x32x2_f32 v[2:17], v125, v23, v[2:17]
	s_cbranch_scc0 .LBB0_2958
	v_mov_b32_e32 v33, 0
	s_andn2_b64 vcc, exec, s[14:15]
	v_mov_b32_e32 v32, v33
	v_mov_b32_e32 v31, v33
	v_mov_b32_e32 v30, v33
	v_mov_b32_e32 v29, v33
	v_mov_b32_e32 v28, v33
	v_mov_b32_e32 v27, v33
	v_mov_b32_e32 v26, v33
	v_mov_b32_e32 v25, v33
	v_mov_b32_e32 v24, v33
	v_mov_b32_e32 v23, v33
	v_mov_b32_e32 v22, v33
	v_mov_b32_e32 v21, v33
	v_mov_b32_e32 v20, v33
	v_mov_b32_e32 v19, v33
	v_mov_b32_e32 v18, v33
	s_cbranch_vccnz .LBB0_2962
	v_mov_b32_e32 v18, 0
	s_mov_b32 s8, 0
	v_mov_b32_e32 v19, v18
	v_mov_b32_e32 v20, v18
	v_mov_b32_e32 v21, v18
	v_mov_b32_e32 v22, v18
	v_mov_b32_e32 v23, v18
	v_mov_b32_e32 v24, v18
	v_mov_b32_e32 v25, v18
	v_mov_b32_e32 v26, v18
	v_mov_b32_e32 v27, v18
	v_mov_b32_e32 v28, v18
	v_mov_b32_e32 v29, v18
	v_mov_b32_e32 v30, v18
	v_mov_b32_e32 v31, v18
	v_mov_b32_e32 v32, v18
	v_mov_b32_e32 v33, v18
.LBB0_2961:
	v_add_u32_e32 v38, s8, v99
	ds_read2_b32 v[34:35], v38 offset1:2
	v_add_u32_e32 v39, s8, v98
	ds_read2_b32 v[36:37], v39 offset1:2
	s_add_i32 s8, s8, 64
	s_cmpk_lg_i32 s8, 0x100
	ds_read2_b32 v[120:121], v38 offset0:4 offset1:6
	ds_read2_b32 v[122:123], v39 offset0:4 offset1:6
	ds_read2_b32 v[124:125], v38 offset0:8 offset1:10
	ds_read2_b32 v[126:127], v39 offset0:8 offset1:10
	ds_read2_b32 v[128:129], v38 offset0:12 offset1:14
	ds_read2_b32 v[130:131], v39 offset0:12 offset1:14
	s_waitcnt lgkmcnt(6)
	v_mfma_f32_32x32x2_f32 v[18:33], v34, v36, v[18:33]
	v_mfma_f32_32x32x2_f32 v[18:33], v35, v37, v[18:33]
	s_waitcnt lgkmcnt(4)
	v_mfma_f32_32x32x2_f32 v[18:33], v120, v122, v[18:33]
	v_mfma_f32_32x32x2_f32 v[18:33], v121, v123, v[18:33]
	s_waitcnt lgkmcnt(2)
	v_mfma_f32_32x32x2_f32 v[18:33], v124, v126, v[18:33]
	v_mfma_f32_32x32x2_f32 v[18:33], v125, v127, v[18:33]
	s_waitcnt lgkmcnt(0)
	v_mfma_f32_32x32x2_f32 v[18:33], v128, v130, v[18:33]
	v_mfma_f32_32x32x2_f32 v[18:33], v129, v131, v[18:33]
	s_cbranch_scc1 .LBB0_2961

.LBB0_2965:
	ds_read2_b32 v[20:21], v18 offset1:2
	ds_read2st64_b32 v[22:23], v19 offset1:4
	s_add_i32 s8, s8, -8
	s_cmp_eq_u32 s8, 0
	ds_read2_b32 v[120:121], v18 offset0:4 offset1:6
	ds_read2st64_b32 v[122:123], v19 offset0:8 offset1:12
	ds_read2_b32 v[124:125], v18 offset0:8 offset1:10
	ds_read2st64_b32 v[126:127], v19 offset0:16 offset1:20
	ds_read2_b32 v[128:129], v18 offset0:12 offset1:14
	ds_read2st64_b32 v[130:131], v19 offset0:24 offset1:28
	s_waitcnt lgkmcnt(6)
	v_mfma_f32_32x32x2_f32 v[2:17], v20, v22, v[2:17]
	v_mfma_f32_32x32x2_f32 v[2:17], v21, v23, v[2:17]
	s_waitcnt lgkmcnt(4)
	v_mfma_f32_32x32x2_f32 v[2:17], v120, v122, v[2:17]
	v_mfma_f32_32x32x2_f32 v[2:17], v121, v123, v[2:17]
	s_waitcnt lgkmcnt(2)
	v_mfma_f32_32x32x2_f32 v[2:17], v124, v126, v[2:17]
	v_mfma_f32_32x32x2_f32 v[2:17], v125, v127, v[2:17]
	v_add_u32_e32 v19, 0x2000, v19
	v_add_u32_e32 v18, 64, v18
	s_waitcnt lgkmcnt(0)
	v_mfma_f32_32x32x2_f32 v[2:17], v128, v130, v[2:17]
	v_mfma_f32_32x32x2_f32 v[2:17], v129, v131, v[2:17]
	s_cbranch_scc0 .LBB0_2965
	v_add_u32_e32 v18, 0xc200, v103
	s_barrier
	s_nop 14
	ds_write2_b32 v18, v2, v3 offset0:64 offset1:196
	v_add_u32_e32 v2, 0xc600, v103
	ds_write2_b32 v2, v4, v5 offset0:72 offset1:204
	v_add_u32_e32 v2, 0xd200, v103
	ds_write2_b32 v2, v6, v7 offset0:96 offset1:228
	v_add_u32_e32 v2, 0xd600, v103
	ds_write2_b32 v2, v8, v9 offset0:104 offset1:236
	v_add_u32_e32 v2, 0xe400, v103
	ds_write2_b32 v2, v10, v11 offset1:132
	v_add_u32_e32 v2, 0xe800, v103
	ds_write2_b32 v2, v12, v13 offset0:8 offset1:140
	v_add_u32_e32 v2, 0xf400, v103
	ds_write2_b32 v2, v14, v15 offset0:32 offset1:164
	v_add_u32_e32 v2, 0xf800, v103
	v_mov_b64_e32 v[18:19], s[0:1]
	ds_write2_b32 v2, v16, v17 offset0:40 offset1:172
	s_waitcnt lgkmcnt(0)
	s_barrier
	ds_read_b128 v[14:17], v95 offset:49920
	ds_read_b128 v[10:13], v95 offset:49936
	ds_read_b128 v[6:9], v95 offset:49952
	ds_read_b128 v[2:5], v95 offset:49968
	s_load_dwordx2 s[98:99], s[0:1], 0xa8
	s_waitcnt vmcnt(0) lgkmcnt(0)
	v_mov_b32_e32 v22, s98
	v_mov_b32_e32 v23, s99
	v_mov_b32_e32 v1, v229
	v_add_u32_e32 v60, s36, v94
	v_mov_b64_e32 v[18:19], s[12:13]
	v_and_b32_e32 v21, 64, v166
	s_lshl_b32 s70, s35, 2
	v_mad_i64_i32 v[18:19], s[8:9], v60, s29, v[18:19]
	v_xor_b32_e32 v20, 1, v166
	v_lshlrev_b32_e32 v42, 2, v54
	v_add_u32_e32 v59, 64, v21
	v_lshl_add_u64 v[18:19], v[18:19], 0, s[70:71]
	v_cmp_lt_i32_e32 vcc, v20, v59
	v_lshl_add_u64 v[30:31], v[18:19], 0, v[42:43]
	s_waitcnt lgkmcnt(0)
	v_mov_b32_e32 v26, v15
	v_cndmask_b32_e32 v20, v166, v20, vcc
	v_add_co_u32_e32 v18, vcc, s4, v30
	v_lshlrev_b32_e32 v61, 2, v20
	s_nop 0
	v_addc_co_u32_e32 v19, vcc, 0, v31, vcc
	global_load_dwordx4 v[18:21], v[18:19], off offset:1184
	v_mov_b32_e32 v27, v11
	v_mov_b32_e32 v24, v14
	v_mov_b32_e32 v25, v10
	v_mov_b32_e32 v36, v7
	v_mov_b32_e32 v37, v3
	v_pk_mul_f32 v[26:27], v[26:27], v[26:27]
	v_mov_b32_e32 v28, v16
	v_mov_b32_e32 v29, v12
	v_mov_b32_e32 v34, v6
	v_mov_b32_e32 v35, v2
	v_pk_mul_f32 v[36:37], v[36:37], v[36:37]
	v_pk_fma_f32 v[24:25], v[24:25], v[24:25], v[26:27]
	v_mov_b32_e32 v32, v17
	v_mov_b32_e32 v33, v13
	v_mov_b32_e32 v38, v8
	v_mov_b32_e32 v39, v4
	v_pk_fma_f32 v[26:27], v[34:35], v[34:35], v[36:37]
	v_pk_fma_f32 v[24:25], v[28:29], v[28:29], v[24:25]
	v_mov_b32_e32 v40, v9
	v_mov_b32_e32 v41, v5
	v_pk_fma_f32 v[26:27], v[38:39], v[38:39], v[26:27]
	v_pk_fma_f32 v[24:25], v[32:33], v[32:33], v[24:25]
	v_pk_fma_f32 v[26:27], v[40:41], v[40:41], v[26:27]
	v_add_f32_e32 v24, v24, v25
	v_add_f32_e32 v24, v24, v26
	v_add_f32_e32 v24, v24, v27
	ds_bpermute_b32 v25, v61, v24
	v_xor_b32_e32 v26, 2, v166
	v_cmp_lt_i32_e32 vcc, v26, v59
	v_lshl_add_u64 v[62:63], v[30:31], 0, s[72:73]
	v_mov_b32_e32 v38, v14
	v_cndmask_b32_e32 v26, v166, v26, vcc
	v_lshlrev_b32_e32 v26, 2, v26
	s_waitcnt lgkmcnt(0)
	v_add_f32_e32 v24, v24, v25
	ds_bpermute_b32 v25, v26, v24
	v_ashrrev_i32_e32 v61, 31, v60
	s_lshl_b32 s70, s35, 1
	s_mov_b64 s[76:77], 0
	s_waitcnt lgkmcnt(0)
	v_add_f32_e32 v32, v24, v25
	v_lshl_add_u64 v[64:65], v[22:23], 0, v[42:43]
	global_load_dwordx4 v[26:29], v[64:65], off
	v_xor_b32_e32 v22, 4, v166
	v_cmp_lt_i32_e32 vcc, v22, v59
	s_nop 1
	v_cndmask_b32_e32 v22, v166, v22, vcc
	v_lshlrev_b32_e32 v22, 2, v22
	ds_bpermute_b32 v33, v22, v32
	global_load_dwordx4 v[22:25], v[64:65], off offset:16
	s_waitcnt lgkmcnt(0)
	v_add_f32_e32 v30, v32, v33
	v_fmamk_f32 v30, v30, 0x3c000000, v104
	v_mul_f32_e32 v31, 0x4f800000, v30
	v_cmp_gt_f32_e32 vcc, s31, v30
	s_nop 1
	v_cndmask_b32_e32 v39, v30, v31, vcc
	v_sqrt_f32_e32 v40, v39
	global_load_dwordx4 v[30:33], v[62:63], off offset:16
	global_load_dwordx4 v[34:37], v[62:63], off offset:48
	v_add_u32_e32 v14, -1, v40
	v_add_u32_e32 v41, 1, v40
	v_fma_f32 v42, -v14, v40, v39
	v_fma_f32 v59, -v41, v40, v39
	v_cmp_ge_f32_e64 s[8:9], 0, v42
	s_nop 1
	v_cndmask_b32_e64 v14, v40, v14, s[8:9]
	v_cmp_lt_f32_e64 s[8:9], 0, v59
	s_nop 1
	v_cndmask_b32_e64 v14, v14, v41, s[8:9]
	v_mul_f32_e32 v40, 0x37800000, v14
	v_cndmask_b32_e32 v14, v14, v40, vcc
	v_cmp_class_f32_e32 vcc, v39, v105
	s_nop 1
	v_cndmask_b32_e32 v14, v14, v39, vcc
	v_div_scale_f32 v40, s[8:9], v14, v14, 1.0
	v_rcp_f32_e32 v41, v40
	v_mov_b32_e32 v39, v16
	v_div_scale_f32 v16, vcc, 1.0, v14, 1.0
	v_fma_f32 v42, -v40, v41, 1.0
	v_fmac_f32_e32 v41, v42, v41
	v_mul_f32_e32 v42, v16, v41
	v_fma_f32 v59, -v40, v42, v16
	v_fmac_f32_e32 v42, v59, v41
	v_fma_f32 v16, -v40, v42, v16
	v_div_fmas_f32 v16, v16, v41, v42
	v_div_fixup_f32 v14, v16, v14, 1.0
	v_pk_mul_f32 v[110:111], v[38:39], v[14:15] op_sel_hi:[1,0]
	s_waitcnt vmcnt(0)
	v_mul_f32_e32 v16, 0xbfb8aa3b, v18
	v_mul_f32_e32 v38, 0xbfb8aa3b, v20
	v_exp_f32_e32 v112, v16
	v_exp_f32_e32 v113, v38
	v_mul_f32_e32 v16, 0xbfb8aa3b, v19
	global_load_dwordx4 v[38:41], v[64:65], off offset:48
	global_load_dwordx4 v[106:109], v[64:65], off offset:32
	v_exp_f32_e32 v64, v16
	v_pk_add_f32 v[112:113], v[112:113], 1.0 op_sel_hi:[1,0]
	s_nop 0
	v_div_scale_f32 v16, s[8:9], v113, v113, v20
	v_rcp_f32_e32 v65, v16
	v_div_scale_f32 v59, s[8:9], v112, v112, v18
	v_rcp_f32_e32 v116, v59
	v_fma_f32 v114, -v16, v65, 1.0
	v_div_scale_f32 v42, vcc, v20, v113, v20
	v_fmac_f32_e32 v65, v114, v65
	v_fma_f32 v115, -v59, v116, 1.0
	v_mul_f32_e32 v114, v42, v65
	v_fmac_f32_e32 v116, v115, v116
	v_fma_f32 v115, -v16, v114, v42
	v_fmac_f32_e32 v114, v115, v65
	v_fma_f32 v16, -v16, v114, v42
	v_div_fmas_f32 v16, v16, v65, v114
	v_div_scale_f32 v117, s[8:9], v18, v112, v18
	v_div_fixup_f32 v113, v16, v113, v20
	v_mul_f32_e32 v20, 0xbfb8aa3b, v21
	v_mul_f32_e32 v118, v117, v116
	v_exp_f32_e32 v65, v20
	v_fma_f32 v119, -v59, v118, v117
	v_fmac_f32_e32 v118, v119, v116
	v_fma_f32 v16, -v59, v118, v117
	s_mov_b64 vcc, s[8:9]
	v_div_fmas_f32 v16, v16, v116, v118
	v_pk_add_f32 v[64:65], v[64:65], 1.0 op_sel_hi:[1,0]
	v_div_fixup_f32 v112, v16, v112, v18
	v_mov_b32_e32 v16, v15
	v_div_scale_f32 v15, s[8:9], v65, v65, v21
	v_rcp_f32_e32 v18, v15
	v_mov_b32_e32 v114, v26
	v_mov_b32_e32 v115, v28
	v_mov_b32_e32 v28, v27
	v_fma_f32 v20, -v15, v18, 1.0
	v_fmac_f32_e32 v18, v20, v18
	v_div_scale_f32 v20, vcc, v21, v65, v21
	v_mul_f32_e32 v26, v20, v18
	v_fma_f32 v27, -v15, v26, v20
	v_fmac_f32_e32 v26, v27, v18
	v_pk_mul_f32 v[16:17], v[16:17], v[14:15] op_sel_hi:[1,0]
	v_fma_f32 v15, -v15, v26, v20
	v_div_scale_f32 v20, s[8:9], v64, v64, v19
	v_rcp_f32_e32 v27, v20
	v_div_fmas_f32 v15, v15, v18, v26
	v_div_fixup_f32 v21, v15, v65, v21
	v_pk_mul_f32 v[16:17], v[28:29], v[16:17]
	v_fma_f32 v15, -v20, v27, 1.0
	v_fmac_f32_e32 v27, v15, v27
	v_div_scale_f32 v15, vcc, v19, v64, v19
	v_mul_f32_e32 v18, v15, v27
	v_fma_f32 v26, -v20, v18, v15
	v_fmac_f32_e32 v18, v26, v27
	v_fma_f32 v15, -v20, v18, v15
	v_div_fmas_f32 v15, v15, v27, v18
	v_div_fixup_f32 v20, v15, v64, v19
	v_pk_mul_f32 v[20:21], v[20:21], v[16:17]
	global_load_dwordx4 v[16:19], v[62:63], off offset:32
	s_waitcnt lgkmcnt(0)
	v_mul_f32_e32 v15, 0xbfb8aa3b, v30
	v_exp_f32_e32 v26, v15
	v_mul_f32_e32 v15, 0xbfb8aa3b, v31
	v_exp_f32_e32 v28, v15
	v_mul_f32_e32 v15, 0xbfb8aa3b, v32
	v_exp_f32_e32 v27, v15
	v_mov_b32_e32 v62, v10
	v_mov_b32_e32 v63, v12
	v_pk_mul_f32 v[62:63], v[62:63], v[14:15] op_sel_hi:[1,0]
	v_pk_add_f32 v[26:27], v[26:27], 1.0 op_sel_hi:[1,0]
	v_mov_b32_e32 v64, v22
	v_div_scale_f32 v10, s[8:9], v27, v27, v32
	v_rcp_f32_e32 v12, v10
	v_mov_b32_e32 v65, v24
	v_pk_mul_f32 v[110:111], v[114:115], v[110:111]
	v_pk_mul_f32 v[62:63], v[62:63], v[64:65]
	v_fma_f32 v15, -v10, v12, 1.0
	v_fmac_f32_e32 v12, v15, v12
	v_div_scale_f32 v15, vcc, v32, v27, v32
	v_mul_f32_e32 v22, v15, v12
	v_fma_f32 v24, -v10, v22, v15
	v_fmac_f32_e32 v22, v24, v12
	v_fma_f32 v10, -v10, v22, v15
	v_div_scale_f32 v15, s[8:9], v26, v26, v30
	v_rcp_f32_e32 v24, v15
	v_div_fmas_f32 v10, v10, v12, v22
	v_div_fixup_f32 v27, v10, v27, v32
	v_pk_mul_f32 v[110:111], v[112:113], v[110:111]
	v_fma_f32 v10, -v15, v24, 1.0
	v_fmac_f32_e32 v24, v10, v24
	v_div_scale_f32 v10, vcc, v30, v26, v30
	v_mul_f32_e32 v12, v10, v24
	v_fma_f32 v22, -v15, v12, v10
	v_fmac_f32_e32 v12, v22, v24
	v_fma_f32 v10, -v15, v12, v10
	v_div_fmas_f32 v10, v10, v24, v12
	v_mul_f32_e32 v12, 0xbfb8aa3b, v33
	v_exp_f32_e32 v29, v12
	v_div_fixup_f32 v26, v10, v26, v30
	v_mov_b32_e32 v12, v11
	v_mov_b32_e32 v24, v23
	v_pk_add_f32 v[10:11], v[28:29], 1.0 op_sel_hi:[1,0]
	v_pk_mul_f32 v[26:27], v[62:63], v[26:27]
	v_div_scale_f32 v15, s[8:9], v11, v11, v33
	v_rcp_f32_e32 v22, v15
	v_pk_mul_f32 v[12:13], v[12:13], v[14:15] op_sel_hi:[1,0]
	v_lshlrev_b32_e32 v42, 1, v54
	v_pk_mul_f32 v[12:13], v[12:13], v[24:25]
	v_fma_f32 v23, -v15, v22, 1.0
	v_fmac_f32_e32 v22, v23, v22
	v_div_scale_f32 v23, vcc, v33, v11, v33
	v_mul_f32_e32 v24, v23, v22
	v_fma_f32 v25, -v15, v24, v23
	v_fmac_f32_e32 v24, v25, v22
	v_fma_f32 v15, -v15, v24, v23
	v_div_scale_f32 v23, s[8:9], v10, v10, v31
	v_rcp_f32_e32 v25, v23
	v_div_fmas_f32 v15, v15, v22, v24
	v_div_fixup_f32 v11, v15, v11, v33
	v_fma_f32 v15, -v23, v25, 1.0
	v_fmac_f32_e32 v25, v15, v25
	v_div_scale_f32 v15, vcc, v31, v10, v31
	v_mul_f32_e32 v22, v15, v25
	v_fma_f32 v24, -v23, v22, v15
	v_fmac_f32_e32 v22, v24, v25
	v_fma_f32 v15, -v23, v22, v15
	v_div_fmas_f32 v15, v15, v25, v22
	v_div_fixup_f32 v10, v15, v10, v31
	v_pk_mul_f32 v[10:11], v[12:13], v[10:11]
	v_cvt_pk_bf16_f32 v13, v27, v11
	v_cvt_pk_bf16_f32 v11, v111, v21
	s_waitcnt vmcnt(0)
	v_mul_f32_e32 v15, 0xbfb8aa3b, v16
	v_cvt_pk_bf16_f32 v12, v26, v10
	v_cvt_pk_bf16_f32 v10, v110, v20
	v_exp_f32_e32 v20, v15
	v_mul_f32_e32 v15, 0xbfb8aa3b, v17
	v_exp_f32_e32 v22, v15
	v_mul_f32_e32 v15, 0xbfb8aa3b, v18
	v_exp_f32_e32 v21, v15
	v_mov_b32_e32 v24, v6
	v_mov_b32_e32 v25, v8
	v_pk_mul_f32 v[24:25], v[24:25], v[14:15] op_sel_hi:[1,0]
	v_pk_add_f32 v[20:21], v[20:21], 1.0 op_sel_hi:[1,0]
	v_mov_b32_e32 v26, v106
	v_div_scale_f32 v6, s[8:9], v21, v21, v18
	v_rcp_f32_e32 v8, v6
	v_mov_b32_e32 v27, v108
	v_pk_mul_f32 v[24:25], v[24:25], v[26:27]
	v_mov_b32_e32 v108, v107
	v_fma_f32 v15, -v6, v8, 1.0
	v_fmac_f32_e32 v8, v15, v8
	v_div_scale_f32 v15, vcc, v18, v21, v18
	v_mul_f32_e32 v23, v15, v8
	v_fma_f32 v26, -v6, v23, v15
	v_fmac_f32_e32 v23, v26, v8
	v_fma_f32 v6, -v6, v23, v15
	v_div_scale_f32 v15, s[8:9], v20, v20, v16
	v_rcp_f32_e32 v26, v15
	v_div_fmas_f32 v6, v6, v8, v23
	v_div_fixup_f32 v21, v6, v21, v18
	v_fma_f32 v6, -v15, v26, 1.0
	v_fmac_f32_e32 v26, v6, v26
	v_div_scale_f32 v6, vcc, v16, v20, v16
	v_mul_f32_e32 v8, v6, v26
	v_fma_f32 v18, -v15, v8, v6
	v_fmac_f32_e32 v8, v18, v26
	v_fma_f32 v6, -v15, v8, v6
	v_div_fmas_f32 v6, v6, v26, v8
	v_mul_f32_e32 v8, 0xbfb8aa3b, v19
	v_exp_f32_e32 v23, v8
	v_div_fixup_f32 v20, v6, v20, v16
	v_mov_b32_e32 v8, v7
	v_pk_mul_f32 v[20:21], v[24:25], v[20:21]
	v_pk_add_f32 v[6:7], v[22:23], 1.0 op_sel_hi:[1,0]
	s_nop 0
	v_div_scale_f32 v15, s[8:9], v7, v7, v19
	v_rcp_f32_e32 v16, v15
	v_pk_mul_f32 v[8:9], v[8:9], v[14:15] op_sel_hi:[1,0]
	v_fma_f32 v18, -v15, v16, 1.0
	v_fmac_f32_e32 v16, v18, v16
	v_div_scale_f32 v18, vcc, v19, v7, v19
	v_mul_f32_e32 v22, v18, v16
	v_fma_f32 v23, -v15, v22, v18
	v_fmac_f32_e32 v22, v23, v16
	v_fma_f32 v15, -v15, v22, v18
	v_div_scale_f32 v18, s[8:9], v6, v6, v17
	v_rcp_f32_e32 v23, v18
	v_div_fmas_f32 v15, v15, v16, v22
	v_div_fixup_f32 v7, v15, v7, v19
	v_pk_mul_f32 v[8:9], v[8:9], v[108:109]
	v_fma_f32 v15, -v18, v23, 1.0
	v_fmac_f32_e32 v23, v15, v23
	v_div_scale_f32 v15, vcc, v17, v6, v17
	v_mul_f32_e32 v16, v15, v23
	v_fma_f32 v19, -v18, v16, v15
	v_fmac_f32_e32 v16, v19, v23
	v_fma_f32 v15, -v18, v16, v15
	v_div_fmas_f32 v15, v15, v23, v16
	v_div_fixup_f32 v6, v15, v6, v17
	v_pk_mul_f32 v[6:7], v[8:9], v[6:7]
	v_mul_f32_e32 v9, 0xbfb8aa3b, v35
	v_mul_f32_e32 v8, 0xbfb8aa3b, v34
	v_exp_f32_e32 v16, v9
	v_mul_f32_e32 v9, 0xbfb8aa3b, v36
	v_exp_f32_e32 v8, v8
	v_exp_f32_e32 v9, v9
	v_mov_b32_e32 v18, v2
	v_mov_b32_e32 v19, v4
	v_pk_mul_f32 v[18:19], v[18:19], v[14:15] op_sel_hi:[1,0]
	v_pk_add_f32 v[8:9], v[8:9], 1.0 op_sel_hi:[1,0]
	v_mov_b32_e32 v22, v38
	v_div_scale_f32 v2, s[8:9], v9, v9, v36
	v_rcp_f32_e32 v4, v2
	v_mov_b32_e32 v23, v40
	v_pk_mul_f32 v[18:19], v[18:19], v[22:23]
	v_mov_b32_e32 v40, v39
	v_fma_f32 v15, -v2, v4, 1.0
	v_fmac_f32_e32 v4, v15, v4
	v_div_scale_f32 v15, vcc, v36, v9, v36
	v_mul_f32_e32 v17, v15, v4
	v_fma_f32 v22, -v2, v17, v15
	v_fmac_f32_e32 v17, v22, v4
	v_fma_f32 v2, -v2, v17, v15
	v_div_scale_f32 v15, s[8:9], v8, v8, v34
	v_rcp_f32_e32 v22, v15
	v_div_fmas_f32 v2, v2, v4, v17
	v_div_fixup_f32 v9, v2, v9, v36
	v_fma_f32 v2, -v15, v22, 1.0
	v_fmac_f32_e32 v22, v2, v22
	v_div_scale_f32 v2, vcc, v34, v8, v34
	v_mul_f32_e32 v4, v2, v22
	v_fma_f32 v17, -v15, v4, v2
	v_fmac_f32_e32 v4, v17, v22
	v_fma_f32 v2, -v15, v4, v2
	v_div_fmas_f32 v2, v2, v22, v4
	v_mul_f32_e32 v4, 0xbfb8aa3b, v37
	v_exp_f32_e32 v17, v4
	v_div_fixup_f32 v8, v2, v8, v34
	v_mov_b32_e32 v4, v3
	v_pk_mul_f32 v[8:9], v[18:19], v[8:9]
	v_pk_add_f32 v[2:3], v[16:17], 1.0 op_sel_hi:[1,0]
	s_nop 0
	v_div_scale_f32 v15, s[8:9], v3, v3, v37
	v_rcp_f32_e32 v16, v15
	v_pk_mul_f32 v[4:5], v[4:5], v[14:15] op_sel_hi:[1,0]
	v_fma_f32 v14, -v15, v16, 1.0
	v_fmac_f32_e32 v16, v14, v16
	v_div_scale_f32 v14, vcc, v37, v3, v37
	v_mul_f32_e32 v17, v14, v16
	v_fma_f32 v18, -v15, v17, v14
	v_fmac_f32_e32 v17, v18, v16
	v_fma_f32 v14, -v15, v17, v14
	v_div_scale_f32 v15, s[8:9], v2, v2, v35
	v_rcp_f32_e32 v18, v15
	v_div_fmas_f32 v14, v14, v16, v17
	v_div_fixup_f32 v3, v14, v3, v37
	v_pk_mul_f32 v[4:5], v[4:5], v[40:41]
	v_fma_f32 v14, -v15, v18, 1.0
	v_fmac_f32_e32 v18, v14, v18
	v_div_scale_f32 v14, vcc, v35, v2, v35
	v_mul_f32_e32 v16, v14, v18
	v_fma_f32 v17, -v15, v16, v14
	v_fmac_f32_e32 v16, v17, v18
	v_fma_f32 v14, -v15, v16, v14
	v_div_fmas_f32 v14, v14, v18, v16
	v_div_fixup_f32 v2, v14, v2, v35
	v_pk_mul_f32 v[2:3], v[4:5], v[2:3]
	v_bfe_u32 v5, v2, 16, 1
	v_add3_u32 v2, v2, v5, s33
	v_bfe_u32 v14, v8, 16, 1
	v_add3_u32 v8, v8, v14, s33
	v_lshrrev_b32_e32 v4, 16, v8
	v_cvt_pk_bf16_f32 v5, v9, v3
	v_and_or_b32 v4, v2, s34, v4
	v_cvt_pk_bf16_f32 v3, v21, v7
	v_cvt_pk_bf16_f32 v2, v20, v6
	v_lshlrev_b64 v[6:7], 11, v[60:61]
	v_lshl_add_u64 v[6:7], s[68:69], 0, v[6:7]
	v_lshl_add_u64 v[6:7], v[6:7], 0, s[70:71]
	v_lshl_add_u64 v[6:7], v[6:7], 0, v[42:43]
	v_lshl_add_u64 v[8:9], v[6:7], 0, s[74:75]
	v_add_co_u32_e32 v6, vcc, 0xdc00000, v6
	s_nop 1
	v_addc_co_u32_e32 v7, vcc, 0, v7, vcc
	global_store_dwordx4 v[6:7], v[10:13], off offset:1024
	global_store_dwordx4 v[8:9], v[2:5], off offset:16
	s_branch .LBB0_2949

.LBB0_5565:
	v_add_u32_e32 v22, s5, v18
	ds_read2_b32 v[20:21], v22 offset1:2
	v_add_u32_e32 v23, s5, v19
	v_add_u32_e32 v24, 0x14300, v23
	v_add_u32_e32 v25, 0x14700, v23
	v_add_u32_e32 v26, 0x14b00, v23
	v_add_u32_e32 v27, 0x14f00, v23
	v_add_u32_e32 v28, 0x15300, v23
	v_add_u32_e32 v29, 0x15700, v23
	v_add_u32_e32 v30, 0x15b00, v23
	v_add_u32_e32 v23, 0x15f00, v23
	ds_read_b32 v24, v24
	ds_read_b32 v25, v25
	ds_read_b32 v26, v26
	ds_read_b32 v27, v27
	ds_read_b32 v28, v28
	ds_read_b32 v29, v29
	ds_read_b32 v30, v30
	ds_read_b32 v23, v23
	ds_read2_b32 v[120:121], v22 offset0:4 offset1:6
	ds_read2_b32 v[122:123], v22 offset0:8 offset1:10
	ds_read2_b32 v[124:125], v22 offset0:12 offset1:14
	s_waitcnt lgkmcnt(10)
	v_mfma_f32_32x32x2_f32 v[2:17], v20, v24, v[2:17]
	s_add_i32 s8, s8, -8
	v_add_u32_e32 v19, 0x2000, v19
	s_cmp_lg_u32 s8, 0
	v_add_u32_e32 v18, 64, v18
	s_waitcnt lgkmcnt(9)
	v_mfma_f32_32x32x2_f32 v[2:17], v21, v25, v[2:17]
	s_waitcnt lgkmcnt(2)
	v_mfma_f32_32x32x2_f32 v[2:17], v120, v26, v[2:17]
	v_mfma_f32_32x32x2_f32 v[2:17], v121, v27, v[2:17]
	s_waitcnt lgkmcnt(1)
	v_mfma_f32_32x32x2_f32 v[2:17], v122, v28, v[2:17]
	v_mfma_f32_32x32x2_f32 v[2:17], v123, v29, v[2:17]
	s_waitcnt lgkmcnt(0)
	v_mfma_f32_32x32x2_f32 v[2:17], v124, v30, v[2:17]
	v_mfma_f32_32x32x2_f32 v[2:17], v125, v23, v[2:17]
	s_cbranch_scc1 .LBB0_5565
	v_mov_b32_e32 v33, 0
	s_andn2_b64 vcc, exec, s[14:15]
	v_mov_b32_e32 v32, v33
	v_mov_b32_e32 v31, v33
	v_mov_b32_e32 v30, v33
	v_mov_b32_e32 v29, v33
	v_mov_b32_e32 v28, v33
	v_mov_b32_e32 v27, v33
	v_mov_b32_e32 v26, v33
	v_mov_b32_e32 v25, v33
	v_mov_b32_e32 v24, v33
	v_mov_b32_e32 v23, v33
	v_mov_b32_e32 v22, v33
	v_mov_b32_e32 v21, v33
	v_mov_b32_e32 v20, v33
	v_mov_b32_e32 v19, v33
	v_mov_b32_e32 v18, v33
	s_cbranch_vccnz .LBB0_5569
	v_mov_b32_e32 v18, 0
	s_mov_b32 s8, 0
	v_mov_b32_e32 v19, v18
	v_mov_b32_e32 v20, v18
	v_mov_b32_e32 v21, v18
	v_mov_b32_e32 v22, v18
	v_mov_b32_e32 v23, v18
	v_mov_b32_e32 v24, v18
	v_mov_b32_e32 v25, v18
	v_mov_b32_e32 v26, v18
	v_mov_b32_e32 v27, v18
	v_mov_b32_e32 v28, v18
	v_mov_b32_e32 v29, v18
	v_mov_b32_e32 v30, v18
	v_mov_b32_e32 v31, v18
	v_mov_b32_e32 v32, v18
	v_mov_b32_e32 v33, v18

.LBB0_5572:
	ds_read2_b32 v[20:21], v18 offset1:2
	ds_read2st64_b32 v[22:23], v19 offset1:4
	s_add_i32 s8, s8, -8
	s_cmp_lg_u32 s8, 0
	ds_read2_b32 v[120:121], v18 offset0:4 offset1:6
	ds_read2st64_b32 v[122:123], v19 offset0:8 offset1:12
	ds_read2_b32 v[124:125], v18 offset0:8 offset1:10
	ds_read2st64_b32 v[126:127], v19 offset0:16 offset1:20
	ds_read2_b32 v[128:129], v18 offset0:12 offset1:14
	ds_read2st64_b32 v[130:131], v19 offset0:24 offset1:28
	s_waitcnt lgkmcnt(6)
	v_mfma_f32_32x32x2_f32 v[2:17], v20, v22, v[2:17]
	v_mfma_f32_32x32x2_f32 v[2:17], v21, v23, v[2:17]
	s_waitcnt lgkmcnt(4)
	v_mfma_f32_32x32x2_f32 v[2:17], v120, v122, v[2:17]
	v_mfma_f32_32x32x2_f32 v[2:17], v121, v123, v[2:17]
	s_waitcnt lgkmcnt(2)
	v_mfma_f32_32x32x2_f32 v[2:17], v124, v126, v[2:17]
	v_mfma_f32_32x32x2_f32 v[2:17], v125, v127, v[2:17]
	v_add_u32_e32 v19, 0x2000, v19
	v_add_u32_e32 v18, 64, v18
	s_waitcnt lgkmcnt(0)
	v_mfma_f32_32x32x2_f32 v[2:17], v128, v130, v[2:17]
	v_mfma_f32_32x32x2_f32 v[2:17], v129, v131, v[2:17]
	s_cbranch_scc1 .LBB0_5572
	v_add_u32_e32 v18, 0xc200, v103
	s_barrier
	s_nop 14
	ds_write2_b32 v18, v2, v3 offset0:64 offset1:196
	v_add_u32_e32 v2, 0xc600, v103
	ds_write2_b32 v2, v4, v5 offset0:72 offset1:204
	v_add_u32_e32 v2, 0xd200, v103
	ds_write2_b32 v2, v6, v7 offset0:96 offset1:228
	v_add_u32_e32 v2, 0xd600, v103
	ds_write2_b32 v2, v8, v9 offset0:104 offset1:236
	v_add_u32_e32 v2, 0xe400, v103
	ds_write2_b32 v2, v10, v11 offset1:132
	v_add_u32_e32 v2, 0xe800, v103
	ds_write2_b32 v2, v12, v13 offset0:8 offset1:140
	v_add_u32_e32 v2, 0xf400, v103
	ds_write2_b32 v2, v14, v15 offset0:32 offset1:164
	v_add_u32_e32 v2, 0xf800, v103
	v_mov_b64_e32 v[18:19], s[0:1]
	ds_write2_b32 v2, v16, v17 offset0:40 offset1:172
	s_waitcnt lgkmcnt(0)
	s_barrier
	ds_read_b128 v[14:17], v95 offset:49920
	ds_read_b128 v[10:13], v95 offset:49936
	ds_read_b128 v[6:9], v95 offset:49952
	ds_read_b128 v[2:5], v95 offset:49968
	s_load_dwordx2 s[98:99], s[0:1], 0xa8
	s_waitcnt vmcnt(0) lgkmcnt(0)
	v_mov_b32_e32 v22, s98
	v_mov_b32_e32 v23, s99
	v_mov_b32_e32 v1, v229
	v_add_u32_e32 v60, s36, v94
	v_mov_b64_e32 v[18:19], s[12:13]
	v_and_b32_e32 v21, 64, v166
	s_lshl_b32 s70, s35, 2
	v_mad_i64_i32 v[18:19], s[8:9], v60, s29, v[18:19]
	v_xor_b32_e32 v20, 1, v166
	v_lshlrev_b32_e32 v42, 2, v54
	v_add_u32_e32 v59, 64, v21
	v_lshl_add_u64 v[18:19], v[18:19], 0, s[70:71]
	v_cmp_lt_i32_e32 vcc, v20, v59
	v_lshl_add_u64 v[30:31], v[18:19], 0, v[42:43]
	s_waitcnt lgkmcnt(0)
	v_mov_b32_e32 v26, v15
	v_cndmask_b32_e32 v20, v166, v20, vcc
	v_add_co_u32_e32 v18, vcc, s28, v30
	v_lshlrev_b32_e32 v61, 2, v20
	s_nop 0
	v_addc_co_u32_e32 v19, vcc, 0, v31, vcc
	global_load_dwordx4 v[18:21], v[18:19], off offset:1184
	v_mov_b32_e32 v27, v11
	v_mov_b32_e32 v24, v14
	v_mov_b32_e32 v25, v10
	v_mov_b32_e32 v36, v7
	v_mov_b32_e32 v37, v3
	v_pk_mul_f32 v[26:27], v[26:27], v[26:27]
	v_mov_b32_e32 v28, v16
	v_mov_b32_e32 v29, v12
	v_mov_b32_e32 v34, v6
	v_mov_b32_e32 v35, v2
	v_pk_mul_f32 v[36:37], v[36:37], v[36:37]
	v_pk_fma_f32 v[24:25], v[24:25], v[24:25], v[26:27]
	v_mov_b32_e32 v32, v17
	v_mov_b32_e32 v33, v13
	v_mov_b32_e32 v38, v8
	v_mov_b32_e32 v39, v4
	v_pk_fma_f32 v[26:27], v[34:35], v[34:35], v[36:37]
	v_pk_fma_f32 v[24:25], v[28:29], v[28:29], v[24:25]
	v_mov_b32_e32 v40, v9
	v_mov_b32_e32 v41, v5
	v_pk_fma_f32 v[26:27], v[38:39], v[38:39], v[26:27]
	v_pk_fma_f32 v[24:25], v[32:33], v[32:33], v[24:25]
	v_pk_fma_f32 v[26:27], v[40:41], v[40:41], v[26:27]
	v_add_f32_e32 v24, v24, v25
	v_add_f32_e32 v24, v24, v26
	v_add_f32_e32 v24, v24, v27
	ds_bpermute_b32 v25, v61, v24
	v_xor_b32_e32 v26, 2, v166
	v_cmp_lt_i32_e32 vcc, v26, v59
	v_lshl_add_u64 v[62:63], v[30:31], 0, s[72:73]
	v_mov_b32_e32 v38, v14
	v_cndmask_b32_e32 v26, v166, v26, vcc
	v_lshlrev_b32_e32 v26, 2, v26
	s_waitcnt lgkmcnt(0)
	v_add_f32_e32 v24, v24, v25
	ds_bpermute_b32 v25, v26, v24
	v_ashrrev_i32_e32 v61, 31, v60
	s_lshl_b32 s70, s35, 1
	s_mov_b64 s[76:77], 0
	s_waitcnt lgkmcnt(0)
	v_add_f32_e32 v32, v24, v25
	v_lshl_add_u64 v[64:65], v[22:23], 0, v[42:43]
	global_load_dwordx4 v[26:29], v[64:65], off offset:512
	v_xor_b32_e32 v22, 4, v166
	v_cmp_lt_i32_e32 vcc, v22, v59
	s_nop 1
	v_cndmask_b32_e32 v22, v166, v22, vcc
	v_lshlrev_b32_e32 v22, 2, v22
	ds_bpermute_b32 v33, v22, v32
	global_load_dwordx4 v[22:25], v[64:65], off offset:528
	s_waitcnt lgkmcnt(0)
	v_add_f32_e32 v30, v32, v33
	v_fmamk_f32 v30, v30, 0x3c000000, v104
	v_mul_f32_e32 v31, 0x4f800000, v30
	v_cmp_gt_f32_e32 vcc, s31, v30
	s_nop 1
	v_cndmask_b32_e32 v39, v30, v31, vcc
	v_sqrt_f32_e32 v40, v39
	global_load_dwordx4 v[30:33], v[62:63], off offset:16
	global_load_dwordx4 v[34:37], v[62:63], off offset:48
	v_add_u32_e32 v14, -1, v40
	v_add_u32_e32 v41, 1, v40
	v_fma_f32 v42, -v14, v40, v39
	v_fma_f32 v59, -v41, v40, v39
	v_cmp_ge_f32_e64 s[8:9], 0, v42
	s_nop 1
	v_cndmask_b32_e64 v14, v40, v14, s[8:9]
	v_cmp_lt_f32_e64 s[8:9], 0, v59
	s_nop 1
	v_cndmask_b32_e64 v14, v14, v41, s[8:9]
	v_mul_f32_e32 v40, 0x37800000, v14
	v_cndmask_b32_e32 v14, v14, v40, vcc
	v_cmp_class_f32_e32 vcc, v39, v105
	s_nop 1
	v_cndmask_b32_e32 v14, v14, v39, vcc
	v_div_scale_f32 v40, s[8:9], v14, v14, 1.0
	v_rcp_f32_e32 v41, v40
	v_mov_b32_e32 v39, v16
	v_div_scale_f32 v16, vcc, 1.0, v14, 1.0
	v_fma_f32 v42, -v40, v41, 1.0
	v_fmac_f32_e32 v41, v42, v41
	v_mul_f32_e32 v42, v16, v41
	v_fma_f32 v59, -v40, v42, v16
	v_fmac_f32_e32 v42, v59, v41
	v_fma_f32 v16, -v40, v42, v16
	v_div_fmas_f32 v16, v16, v41, v42
	v_div_fixup_f32 v14, v16, v14, 1.0
	v_pk_mul_f32 v[110:111], v[38:39], v[14:15] op_sel_hi:[1,0]
	s_waitcnt vmcnt(0)
	v_mul_f32_e32 v16, 0xbfb8aa3b, v18
	v_mul_f32_e32 v38, 0xbfb8aa3b, v20
	v_exp_f32_e32 v112, v16
	v_exp_f32_e32 v113, v38
	v_mul_f32_e32 v16, 0xbfb8aa3b, v19
	global_load_dwordx4 v[38:41], v[64:65], off offset:560
	global_load_dwordx4 v[106:109], v[64:65], off offset:544
	v_exp_f32_e32 v64, v16
	v_pk_add_f32 v[112:113], v[112:113], 1.0 op_sel_hi:[1,0]
	s_nop 0
	v_div_scale_f32 v16, s[8:9], v113, v113, v20
	v_rcp_f32_e32 v65, v16
	v_div_scale_f32 v59, s[8:9], v112, v112, v18
	v_rcp_f32_e32 v116, v59
	v_fma_f32 v114, -v16, v65, 1.0
	v_div_scale_f32 v42, vcc, v20, v113, v20
	v_fmac_f32_e32 v65, v114, v65
	v_fma_f32 v115, -v59, v116, 1.0
	v_mul_f32_e32 v114, v42, v65
	v_fmac_f32_e32 v116, v115, v116
	v_fma_f32 v115, -v16, v114, v42
	v_fmac_f32_e32 v114, v115, v65
	v_fma_f32 v16, -v16, v114, v42
	v_div_fmas_f32 v16, v16, v65, v114
	v_div_scale_f32 v117, s[8:9], v18, v112, v18
	v_div_fixup_f32 v113, v16, v113, v20
	v_mul_f32_e32 v20, 0xbfb8aa3b, v21
	v_mul_f32_e32 v118, v117, v116
	v_exp_f32_e32 v65, v20
	v_fma_f32 v119, -v59, v118, v117
	v_fmac_f32_e32 v118, v119, v116
	v_fma_f32 v16, -v59, v118, v117
	s_mov_b64 vcc, s[8:9]
	v_div_fmas_f32 v16, v16, v116, v118
	v_pk_add_f32 v[64:65], v[64:65], 1.0 op_sel_hi:[1,0]
	v_div_fixup_f32 v112, v16, v112, v18
	v_mov_b32_e32 v16, v15
	v_div_scale_f32 v15, s[8:9], v65, v65, v21
	v_rcp_f32_e32 v18, v15
	v_mov_b32_e32 v114, v26
	v_mov_b32_e32 v115, v28
	v_mov_b32_e32 v28, v27
	v_fma_f32 v20, -v15, v18, 1.0
	v_fmac_f32_e32 v18, v20, v18
	v_div_scale_f32 v20, vcc, v21, v65, v21
	v_mul_f32_e32 v26, v20, v18
	v_fma_f32 v27, -v15, v26, v20
	v_fmac_f32_e32 v26, v27, v18
	v_pk_mul_f32 v[16:17], v[16:17], v[14:15] op_sel_hi:[1,0]
	v_fma_f32 v15, -v15, v26, v20
	v_div_scale_f32 v20, s[8:9], v64, v64, v19
	v_rcp_f32_e32 v27, v20
	v_div_fmas_f32 v15, v15, v18, v26
	v_div_fixup_f32 v21, v15, v65, v21
	v_pk_mul_f32 v[16:17], v[28:29], v[16:17]
	v_fma_f32 v15, -v20, v27, 1.0
	v_fmac_f32_e32 v27, v15, v27
	v_div_scale_f32 v15, vcc, v19, v64, v19
	v_mul_f32_e32 v18, v15, v27
	v_fma_f32 v26, -v20, v18, v15
	v_fmac_f32_e32 v18, v26, v27
	v_fma_f32 v15, -v20, v18, v15
	v_div_fmas_f32 v15, v15, v27, v18
	v_div_fixup_f32 v20, v15, v64, v19
	v_pk_mul_f32 v[20:21], v[20:21], v[16:17]
	global_load_dwordx4 v[16:19], v[62:63], off offset:32
	s_waitcnt lgkmcnt(0)
	v_mul_f32_e32 v15, 0xbfb8aa3b, v30
	v_exp_f32_e32 v26, v15
	v_mul_f32_e32 v15, 0xbfb8aa3b, v31
	v_exp_f32_e32 v28, v15
	v_mul_f32_e32 v15, 0xbfb8aa3b, v32
	v_exp_f32_e32 v27, v15
	v_mov_b32_e32 v62, v10
	v_mov_b32_e32 v63, v12
	v_pk_mul_f32 v[62:63], v[62:63], v[14:15] op_sel_hi:[1,0]
	v_pk_add_f32 v[26:27], v[26:27], 1.0 op_sel_hi:[1,0]
	v_mov_b32_e32 v64, v22
	v_div_scale_f32 v10, s[8:9], v27, v27, v32
	v_rcp_f32_e32 v12, v10
	v_mov_b32_e32 v65, v24
	v_pk_mul_f32 v[110:111], v[114:115], v[110:111]
	v_pk_mul_f32 v[62:63], v[62:63], v[64:65]
	v_fma_f32 v15, -v10, v12, 1.0
	v_fmac_f32_e32 v12, v15, v12
	v_div_scale_f32 v15, vcc, v32, v27, v32
	v_mul_f32_e32 v22, v15, v12
	v_fma_f32 v24, -v10, v22, v15
	v_fmac_f32_e32 v22, v24, v12
	v_fma_f32 v10, -v10, v22, v15
	v_div_scale_f32 v15, s[8:9], v26, v26, v30
	v_rcp_f32_e32 v24, v15
	v_div_fmas_f32 v10, v10, v12, v22
	v_div_fixup_f32 v27, v10, v27, v32
	v_pk_mul_f32 v[110:111], v[112:113], v[110:111]
	v_fma_f32 v10, -v15, v24, 1.0
	v_fmac_f32_e32 v24, v10, v24
	v_div_scale_f32 v10, vcc, v30, v26, v30
	v_mul_f32_e32 v12, v10, v24
	v_fma_f32 v22, -v15, v12, v10
	v_fmac_f32_e32 v12, v22, v24
	v_fma_f32 v10, -v15, v12, v10
	v_div_fmas_f32 v10, v10, v24, v12
	v_mul_f32_e32 v12, 0xbfb8aa3b, v33
	v_exp_f32_e32 v29, v12
	v_div_fixup_f32 v26, v10, v26, v30
	v_mov_b32_e32 v12, v11
	v_mov_b32_e32 v24, v23
	v_pk_add_f32 v[10:11], v[28:29], 1.0 op_sel_hi:[1,0]
	v_pk_mul_f32 v[26:27], v[62:63], v[26:27]
	v_div_scale_f32 v15, s[8:9], v11, v11, v33
	v_rcp_f32_e32 v22, v15
	v_pk_mul_f32 v[12:13], v[12:13], v[14:15] op_sel_hi:[1,0]
	v_lshlrev_b32_e32 v42, 1, v54
	v_pk_mul_f32 v[12:13], v[12:13], v[24:25]
	v_fma_f32 v23, -v15, v22, 1.0
	v_fmac_f32_e32 v22, v23, v22
	v_div_scale_f32 v23, vcc, v33, v11, v33
	v_mul_f32_e32 v24, v23, v22
	v_fma_f32 v25, -v15, v24, v23
	v_fmac_f32_e32 v24, v25, v22
	v_fma_f32 v15, -v15, v24, v23
	v_div_scale_f32 v23, s[8:9], v10, v10, v31
	v_rcp_f32_e32 v25, v23
	v_div_fmas_f32 v15, v15, v22, v24
	v_div_fixup_f32 v11, v15, v11, v33
	v_fma_f32 v15, -v23, v25, 1.0
	v_fmac_f32_e32 v25, v15, v25
	v_div_scale_f32 v15, vcc, v31, v10, v31
	v_mul_f32_e32 v22, v15, v25
	v_fma_f32 v24, -v23, v22, v15
	v_fmac_f32_e32 v22, v24, v25
	v_fma_f32 v15, -v23, v22, v15
	v_div_fmas_f32 v15, v15, v25, v22
	v_div_fixup_f32 v10, v15, v10, v31
	v_pk_mul_f32 v[10:11], v[12:13], v[10:11]
	v_cvt_pk_bf16_f32 v13, v27, v11
	v_cvt_pk_bf16_f32 v11, v111, v21
	s_waitcnt vmcnt(0)
	v_mul_f32_e32 v15, 0xbfb8aa3b, v16
	v_cvt_pk_bf16_f32 v12, v26, v10
	v_cvt_pk_bf16_f32 v10, v110, v20
	v_exp_f32_e32 v20, v15
	v_mul_f32_e32 v15, 0xbfb8aa3b, v17
	v_exp_f32_e32 v22, v15
	v_mul_f32_e32 v15, 0xbfb8aa3b, v18
	v_exp_f32_e32 v21, v15
	v_mov_b32_e32 v24, v6
	v_mov_b32_e32 v25, v8
	v_pk_mul_f32 v[24:25], v[24:25], v[14:15] op_sel_hi:[1,0]
	v_pk_add_f32 v[20:21], v[20:21], 1.0 op_sel_hi:[1,0]
	v_mov_b32_e32 v26, v106
	v_div_scale_f32 v6, s[8:9], v21, v21, v18
	v_rcp_f32_e32 v8, v6
	v_mov_b32_e32 v27, v108
	v_pk_mul_f32 v[24:25], v[24:25], v[26:27]
	v_mov_b32_e32 v108, v107
	v_fma_f32 v15, -v6, v8, 1.0
	v_fmac_f32_e32 v8, v15, v8
	v_div_scale_f32 v15, vcc, v18, v21, v18
	v_mul_f32_e32 v23, v15, v8
	v_fma_f32 v26, -v6, v23, v15
	v_fmac_f32_e32 v23, v26, v8
	v_fma_f32 v6, -v6, v23, v15
	v_div_scale_f32 v15, s[8:9], v20, v20, v16
	v_rcp_f32_e32 v26, v15
	v_div_fmas_f32 v6, v6, v8, v23
	v_div_fixup_f32 v21, v6, v21, v18
	v_fma_f32 v6, -v15, v26, 1.0
	v_fmac_f32_e32 v26, v6, v26
	v_div_scale_f32 v6, vcc, v16, v20, v16
	v_mul_f32_e32 v8, v6, v26
	v_fma_f32 v18, -v15, v8, v6
	v_fmac_f32_e32 v8, v18, v26
	v_fma_f32 v6, -v15, v8, v6
	v_div_fmas_f32 v6, v6, v26, v8
	v_mul_f32_e32 v8, 0xbfb8aa3b, v19
	v_exp_f32_e32 v23, v8
	v_div_fixup_f32 v20, v6, v20, v16
	v_mov_b32_e32 v8, v7
	v_pk_mul_f32 v[20:21], v[24:25], v[20:21]
	v_pk_add_f32 v[6:7], v[22:23], 1.0 op_sel_hi:[1,0]
	s_nop 0
	v_div_scale_f32 v15, s[8:9], v7, v7, v19
	v_rcp_f32_e32 v16, v15
	v_pk_mul_f32 v[8:9], v[8:9], v[14:15] op_sel_hi:[1,0]
	v_fma_f32 v18, -v15, v16, 1.0
	v_fmac_f32_e32 v16, v18, v16
	v_div_scale_f32 v18, vcc, v19, v7, v19
	v_mul_f32_e32 v22, v18, v16
	v_fma_f32 v23, -v15, v22, v18
	v_fmac_f32_e32 v22, v23, v16
	v_fma_f32 v15, -v15, v22, v18
	v_div_scale_f32 v18, s[8:9], v6, v6, v17
	v_rcp_f32_e32 v23, v18
	v_div_fmas_f32 v15, v15, v16, v22
	v_div_fixup_f32 v7, v15, v7, v19
	v_pk_mul_f32 v[8:9], v[8:9], v[108:109]
	v_fma_f32 v15, -v18, v23, 1.0
	v_fmac_f32_e32 v23, v15, v23
	v_div_scale_f32 v15, vcc, v17, v6, v17
	v_mul_f32_e32 v16, v15, v23
	v_fma_f32 v19, -v18, v16, v15
	v_fmac_f32_e32 v16, v19, v23
	v_fma_f32 v15, -v18, v16, v15
	v_div_fmas_f32 v15, v15, v23, v16
	v_div_fixup_f32 v6, v15, v6, v17
	v_pk_mul_f32 v[6:7], v[8:9], v[6:7]
	v_mul_f32_e32 v9, 0xbfb8aa3b, v35
	v_mul_f32_e32 v8, 0xbfb8aa3b, v34
	v_exp_f32_e32 v16, v9
	v_mul_f32_e32 v9, 0xbfb8aa3b, v36
	v_exp_f32_e32 v8, v8
	v_exp_f32_e32 v9, v9
	v_mov_b32_e32 v18, v2
	v_mov_b32_e32 v19, v4
	v_pk_mul_f32 v[18:19], v[18:19], v[14:15] op_sel_hi:[1,0]
	v_pk_add_f32 v[8:9], v[8:9], 1.0 op_sel_hi:[1,0]
	v_mov_b32_e32 v22, v38
	v_div_scale_f32 v2, s[8:9], v9, v9, v36
	v_rcp_f32_e32 v4, v2
	v_mov_b32_e32 v23, v40
	v_pk_mul_f32 v[18:19], v[18:19], v[22:23]
	v_mov_b32_e32 v40, v39
	v_fma_f32 v15, -v2, v4, 1.0
	v_fmac_f32_e32 v4, v15, v4
	v_div_scale_f32 v15, vcc, v36, v9, v36
	v_mul_f32_e32 v17, v15, v4
	v_fma_f32 v22, -v2, v17, v15
	v_fmac_f32_e32 v17, v22, v4
	v_fma_f32 v2, -v2, v17, v15
	v_div_scale_f32 v15, s[8:9], v8, v8, v34
	v_rcp_f32_e32 v22, v15
	v_div_fmas_f32 v2, v2, v4, v17
	v_div_fixup_f32 v9, v2, v9, v36
	v_fma_f32 v2, -v15, v22, 1.0
	v_fmac_f32_e32 v22, v2, v22
	v_div_scale_f32 v2, vcc, v34, v8, v34
	v_mul_f32_e32 v4, v2, v22
	v_fma_f32 v17, -v15, v4, v2
	v_fmac_f32_e32 v4, v17, v22
	v_fma_f32 v2, -v15, v4, v2
	v_div_fmas_f32 v2, v2, v22, v4
	v_mul_f32_e32 v4, 0xbfb8aa3b, v37
	v_exp_f32_e32 v17, v4
	v_div_fixup_f32 v8, v2, v8, v34
	v_mov_b32_e32 v4, v3
	v_pk_mul_f32 v[8:9], v[18:19], v[8:9]
	v_pk_add_f32 v[2:3], v[16:17], 1.0 op_sel_hi:[1,0]
	s_nop 0
	v_div_scale_f32 v15, s[8:9], v3, v3, v37
	v_rcp_f32_e32 v16, v15
	v_pk_mul_f32 v[4:5], v[4:5], v[14:15] op_sel_hi:[1,0]
	v_fma_f32 v14, -v15, v16, 1.0
	v_fmac_f32_e32 v16, v14, v16
	v_div_scale_f32 v14, vcc, v37, v3, v37
	v_mul_f32_e32 v17, v14, v16
	v_fma_f32 v18, -v15, v17, v14
	v_fmac_f32_e32 v17, v18, v16
	v_fma_f32 v14, -v15, v17, v14
	v_div_scale_f32 v15, s[8:9], v2, v2, v35
	v_rcp_f32_e32 v18, v15
	v_div_fmas_f32 v14, v14, v16, v17
	v_div_fixup_f32 v3, v14, v3, v37
	v_pk_mul_f32 v[4:5], v[4:5], v[40:41]
	v_fma_f32 v14, -v15, v18, 1.0
	v_fmac_f32_e32 v18, v14, v18
	v_div_scale_f32 v14, vcc, v35, v2, v35
	v_mul_f32_e32 v16, v14, v18
	v_fma_f32 v17, -v15, v16, v14
	v_fmac_f32_e32 v16, v17, v18
	v_fma_f32 v14, -v15, v16, v14
	v_div_fmas_f32 v14, v14, v18, v16
	v_div_fixup_f32 v2, v14, v2, v35
	v_pk_mul_f32 v[2:3], v[4:5], v[2:3]
	v_bfe_u32 v5, v2, 16, 1
	v_add3_u32 v2, v2, v5, s33
	v_bfe_u32 v14, v8, 16, 1
	v_add3_u32 v8, v8, v14, s33
	v_lshrrev_b32_e32 v4, 16, v8
	v_cvt_pk_bf16_f32 v5, v9, v3
	v_and_or_b32 v4, v2, s34, v4
	v_cvt_pk_bf16_f32 v3, v21, v7
	v_cvt_pk_bf16_f32 v2, v20, v6
	v_lshlrev_b64 v[6:7], 11, v[60:61]
	v_lshl_add_u64 v[6:7], s[68:69], 0, v[6:7]
	v_lshl_add_u64 v[6:7], v[6:7], 0, s[70:71]
	v_lshl_add_u64 v[6:7], v[6:7], 0, v[42:43]
	v_lshl_add_u64 v[8:9], v[6:7], 0, s[74:75]
	v_add_co_u32_e32 v6, vcc, 0xdc00000, v6
	s_nop 1
	v_addc_co_u32_e32 v7, vcc, 0, v7, vcc
	global_store_dwordx4 v[6:7], v[10:13], off offset:1024
	global_store_dwordx4 v[8:9], v[2:5], off offset:16
	s_branch .LBB0_5556
